# speedup vs baseline: 1.0207x; 1.0192x over previous
.LBB0_186:
	s_or_b64 exec, exec, s[44:45]
	v_lshlrev_b32_e32 v7, 6, v157
	v_mov_b32_e32 v131, v129
	v_lshlrev_b32_e32 v21, 2, v157
	v_lshlrev_b32_e32 v22, 13, v6
	v_and_b32_e32 v6, 0x3000, v7
	v_add_u32_e32 v168, 0x18000, v158
	v_lshl_add_u64 v[8:9], s[88:89], 0, v[128:129]
	v_lshl_add_u64 v[16:17], s[2:3], 0, v[128:129]
	v_lshl_add_u64 v[18:19], s[2:3], 0, v[130:131]
	v_and_b32_e32 v20, 0x3c0, v7
	v_and_b32_e32 v21, 32, v21
	v_or_b32_e32 v23, 0x10000, v6
	v_and_b32_e32 v6, 48, v157
	v_readfirstlane_b32 s3, v168
	v_add_u32_e32 v169, 0x1a000, v158
	v_lshl_add_u64 v[10:11], s[88:89], 0, v[130:131]
	v_bitop3_b32 v20, v20, v21, v6 bitop3:0x36
	v_lshl_add_u64 v[6:7], v[8:9], 0, s[72:73]
	s_mov_b32 m0, s3
	v_readfirstlane_b32 s3, v169
	v_add_u32_e32 v170, 0x8000, v158
	v_lshl_add_u64 v[12:13], s[94:95], 0, v[128:129]
	s_waitcnt vmcnt(4)
	s_barrier
	global_load_lds_dwordx4 v[6:7], off
	v_lshl_add_u64 v[6:7], v[10:11], 0, s[72:73]
	s_mov_b32 m0, s3
	v_readfirstlane_b32 s3, v170
	v_add_u32_e32 v171, 0xa000, v158
	v_lshl_add_u64 v[14:15], s[94:95], 0, v[130:131]
	global_load_lds_dwordx4 v[6:7], off
	v_lshl_add_u64 v[6:7], v[12:13], 0, s[72:73]
	s_mov_b32 m0, s3
	v_readfirstlane_b32 s3, v171
	v_add_u32_e32 v172, 0x1c000, v158
	global_load_lds_dwordx4 v[6:7], off
	v_lshl_add_u64 v[6:7], v[14:15], 0, s[72:73]
	s_mov_b32 m0, s3
	v_readfirstlane_b32 s3, v172
	v_add_u32_e32 v173, 0x1e000, v158
	global_load_lds_dwordx4 v[6:7], off
	v_lshl_add_u64 v[6:7], v[16:17], 0, s[72:73]
	s_mov_b32 m0, s3
	v_readfirstlane_b32 s3, v173
	global_load_lds_dwordx4 v[6:7], off
	v_lshl_add_u64 v[6:7], v[18:19], 0, s[72:73]
	s_mov_b32 m0, s3
	s_lshl_b64 s[94:95], s[92:93], 1
	global_load_lds_dwordx4 v[6:7], off
	s_lshr_b64 s[44:45], s[92:93], 31
	s_lshr_b32 s2, s53, 6
	s_mul_i32 s44, s44, s53
	s_mul_hi_u32 s45, s94, s53
	s_xor_b64 s[4:5], s[4:5], -1
	s_add_i32 s3, s2, -2
	s_add_i32 s45, s45, s44
	s_mul_i32 s44, s94, s53
	v_add_u32_e32 v0, v2, v0
	s_add_u32 s44, s42, s44
	v_add_u32_e32 v2, v5, v3
	v_add_lshl_u32 v0, v0, v1, 1
	v_mov_b32_e32 v1, v129
	s_addc_u32 s45, s43, s45
	v_add_lshl_u32 v2, v2, v4, 1
	v_mov_b32_e32 v3, v129
	v_lshl_add_u64 v[132:133], s[44:45], 0, v[0:1]
	v_lshl_add_u64 v[134:135], s[44:45], 0, v[2:3]
	s_mul_i32 s44, s66, s53
	s_mul_hi_u32 s45, s91, s53
	s_add_i32 s45, s45, s44
	s_mul_i32 s44, s91, s53
	s_lshl_b64 s[44:45], s[44:45], 1
	s_add_u32 s44, s34, s44
	s_addc_u32 s45, s35, s45
	v_lshl_add_u64 v[136:137], s[44:45], 0, v[0:1]
	v_lshl_add_u64 v[138:139], s[44:45], 0, v[2:3]
	s_add_u32 s44, s92, 0x80
	s_addc_u32 s45, s93, 0
	s_mul_i32 s45, s45, s53
	s_mul_hi_u32 s69, s44, s53
	s_add_i32 s45, s69, s45
	s_mul_i32 s44, s44, s53
	s_lshl_b64 s[44:45], s[44:45], 1
	s_add_u32 s42, s42, s44
	s_addc_u32 s43, s43, s45
	v_lshl_add_u64 v[140:141], s[42:43], 0, v[0:1]
	v_lshl_add_u64 v[142:143], s[42:43], 0, v[2:3]
	s_add_u32 s42, s91, 0x80
	s_addc_u32 s43, s66, 0
	s_mul_i32 s43, s43, s53
	s_mul_hi_u32 s44, s42, s53
	s_add_i32 s43, s44, s43
	s_mul_i32 s42, s42, s53
	s_lshl_b64 s[42:43], s[42:43], 1
	s_add_u32 s34, s34, s42
	s_waitcnt vmcnt(6)
	s_addc_u32 s35, s35, s43
	v_lshl_add_u64 v[144:145], s[34:35], 0, v[0:1]
	v_mov_b32_e32 v0, 0
	v_lshl_add_u64 v[146:147], s[34:35], 0, v[2:3]
	s_lshl_b32 s44, s53, 8
	s_add_u32 s76, s54, 0x80
	s_addc_u32 s77, s55, 0
	s_sub_u32 s72, s54, s44
	s_subb_u32 s73, s55, 0
	s_add_u32 s72, s72, 0x100
	s_addc_u32 s73, s73, 0
	s_add_u32 s42, s88, 0x100
	s_addc_u32 s43, s89, 0
	s_add_u32 s78, s88, s44
	s_addc_u32 s79, s89, 0
	s_add_u32 s78, s78, 0x100
	s_addc_u32 s79, s79, 0
	s_mov_b32 s34, 0
	v_readfirstlane_b32 s35, v158
	v_add_u32_e32 v174, 0xc000, v158
	v_add_u32_e32 v175, 0xe000, v158
	v_add_u32_e32 v164, v23, v20
	v_add_u32_e32 v162, v22, v20
	v_mov_b32_e32 v1, v0
	v_mov_b32_e32 v2, v0
	v_mov_b32_e32 v3, v0
	v_mov_b32_e32 v4, v0
	v_mov_b32_e32 v5, v0
	v_mov_b32_e32 v6, v0
	v_mov_b32_e32 v7, v0
	v_mov_b32_e32 v8, v0
	v_mov_b32_e32 v9, v0
	v_mov_b32_e32 v10, v0
	v_mov_b32_e32 v11, v0
	v_mov_b32_e32 v12, v0
	v_mov_b32_e32 v13, v0
	v_mov_b32_e32 v14, v0
	v_mov_b32_e32 v15, v0
	v_mov_b32_e32 v16, v0
	v_mov_b32_e32 v17, v0
	v_mov_b32_e32 v18, v0
	v_mov_b32_e32 v19, v0
	v_mov_b32_e32 v20, v0
	v_mov_b32_e32 v21, v0
	v_mov_b32_e32 v22, v0
	v_mov_b32_e32 v23, v0
	v_mov_b32_e32 v24, v0
	v_mov_b32_e32 v25, v0
	v_mov_b32_e32 v26, v0
	v_mov_b32_e32 v27, v0
	v_mov_b32_e32 v28, v0
	v_mov_b32_e32 v29, v0
	v_mov_b32_e32 v30, v0
	v_mov_b32_e32 v31, v0
	v_mov_b32_e32 v32, v0
	v_mov_b32_e32 v33, v0
	v_mov_b32_e32 v34, v0
	v_mov_b32_e32 v35, v0
	v_mov_b32_e32 v36, v0
	v_mov_b32_e32 v37, v0
	v_mov_b32_e32 v38, v0
	v_mov_b32_e32 v39, v0
	v_mov_b32_e32 v40, v0
	v_mov_b32_e32 v41, v0
	v_mov_b32_e32 v42, v0
	v_mov_b32_e32 v43, v0
	v_mov_b32_e32 v44, v0
	v_mov_b32_e32 v45, v0
	v_mov_b32_e32 v46, v0
	v_mov_b32_e32 v47, v0
	v_mov_b32_e32 v48, v0
	v_mov_b32_e32 v49, v0
	v_mov_b32_e32 v50, v0
	v_mov_b32_e32 v51, v0
	v_mov_b32_e32 v52, v0
	v_mov_b32_e32 v53, v0
	v_mov_b32_e32 v54, v0
	v_mov_b32_e32 v55, v0
	v_mov_b32_e32 v56, v0
	v_mov_b32_e32 v57, v0
	v_mov_b32_e32 v58, v0
	v_mov_b32_e32 v59, v0
	v_mov_b32_e32 v60, v0
	v_mov_b32_e32 v61, v0
	v_mov_b32_e32 v62, v0
	v_mov_b32_e32 v63, v0
	v_mov_b32_e32 v64, v0
	v_mov_b32_e32 v65, v0
	v_mov_b32_e32 v66, v0
	v_mov_b32_e32 v67, v0
	v_mov_b32_e32 v68, v0
	v_mov_b32_e32 v69, v0
	v_mov_b32_e32 v70, v0
	v_mov_b32_e32 v71, v0
	v_mov_b32_e32 v72, v0
	v_mov_b32_e32 v73, v0
	v_mov_b32_e32 v74, v0
	v_mov_b32_e32 v75, v0
	v_mov_b32_e32 v76, v0
	v_mov_b32_e32 v77, v0
	v_mov_b32_e32 v78, v0
	v_mov_b32_e32 v79, v0
	v_mov_b32_e32 v80, v0
	v_mov_b32_e32 v81, v0
	v_mov_b32_e32 v82, v0
	v_mov_b32_e32 v83, v0
	v_mov_b32_e32 v84, v0
	v_mov_b32_e32 v85, v0
	v_mov_b32_e32 v86, v0
	v_mov_b32_e32 v87, v0
	v_mov_b32_e32 v88, v0
	v_mov_b32_e32 v89, v0
	v_mov_b32_e32 v90, v0
	v_mov_b32_e32 v91, v0
	v_mov_b32_e32 v92, v0
	v_mov_b32_e32 v93, v0
	v_mov_b32_e32 v94, v0
	v_mov_b32_e32 v95, v0
	v_mov_b32_e32 v96, v0
	v_mov_b32_e32 v97, v0
	v_mov_b32_e32 v98, v0
	v_mov_b32_e32 v99, v0
	v_mov_b32_e32 v100, v0
	v_mov_b32_e32 v101, v0
	v_mov_b32_e32 v102, v0
	v_mov_b32_e32 v103, v0
	v_mov_b32_e32 v104, v0
	v_mov_b32_e32 v105, v0
	v_mov_b32_e32 v106, v0
	v_mov_b32_e32 v107, v0
	v_mov_b32_e32 v108, v0
	v_mov_b32_e32 v109, v0
	v_mov_b32_e32 v110, v0
	v_mov_b32_e32 v111, v0
	v_mov_b32_e32 v112, v0
	v_mov_b32_e32 v113, v0
	v_mov_b32_e32 v114, v0
	v_mov_b32_e32 v115, v0
	v_mov_b32_e32 v116, v0
	v_mov_b32_e32 v117, v0
	v_mov_b32_e32 v118, v0
	v_mov_b32_e32 v119, v0
	v_mov_b32_e32 v120, v0
	v_mov_b32_e32 v121, v0
	v_mov_b32_e32 v122, v0
	v_mov_b32_e32 v123, v0
	v_mov_b32_e32 v124, v0
	v_mov_b32_e32 v125, v0
	v_mov_b32_e32 v126, v0
	v_mov_b32_e32 v127, v0
	s_barrier
	v_readfirstlane_b32 s44, v157
	s_nop 3
	s_cmp_ge_u32 s44, 0x100
	s_cbranch_scc0 .Lgemm_noprio
	s_setprio 1
.Lgemm_noprio:
.LBB0_187:
	s_add_u32 m0, s35, 0xc000
	ds_read_b128 v[176:179], v164
	ds_read_b128 v[180:183], v164 offset:1024
	ds_read_b128 v[184:187], v164 offset:2048
	ds_read_b128 v[188:191], v164 offset:3072
	ds_read_b128 v[192:195], v162
	ds_read_b128 v[196:199], v162 offset:1024
	ds_read_b128 v[200:203], v162 offset:2048
	ds_read_b128 v[204:207], v162 offset:3072
	ds_read_b128 v[208:211], v162 offset:4096
	ds_read_b128 v[212:215], v162 offset:5120
	ds_read_b128 v[216:219], v162 offset:6144
	ds_read_b128 v[220:223], v162 offset:7168
	global_load_lds_dwordx4 v128, s[76:77]
	s_add_u32 m0, s35, 0xe000
	s_nop 0
	global_load_lds_dwordx4 v130, s[76:77]
	s_add_u32 s76, s76, 0x80
	s_addc_u32 s77, s77, 0
	s_waitcnt lgkmcnt(8)
	s_barrier
	s_waitcnt lgkmcnt(0)
	v_mfma_f32_16x16x32_bf16 v[124:127], v[176:179], v[192:195], v[124:127]
	v_mfma_f32_16x16x32_bf16 v[120:123], v[184:187], v[192:195], v[120:123]
	v_mfma_f32_16x16x32_bf16 v[116:119], v[176:179], v[200:203], v[116:119]
	v_mfma_f32_16x16x32_bf16 v[112:115], v[184:187], v[200:203], v[112:115]
	v_mfma_f32_16x16x32_bf16 v[108:111], v[176:179], v[208:211], v[108:111]
	v_mfma_f32_16x16x32_bf16 v[104:107], v[184:187], v[208:211], v[104:107]
	v_mfma_f32_16x16x32_bf16 v[100:103], v[176:179], v[216:219], v[100:103]
	v_mfma_f32_16x16x32_bf16 v[96:99], v[184:187], v[216:219], v[96:99]
	v_mfma_f32_16x16x32_bf16 v[124:127], v[180:183], v[196:199], v[124:127]
	v_mfma_f32_16x16x32_bf16 v[120:123], v[188:191], v[196:199], v[120:123]
	v_mfma_f32_16x16x32_bf16 v[116:119], v[180:183], v[204:207], v[116:119]
	v_mfma_f32_16x16x32_bf16 v[112:115], v[188:191], v[204:207], v[112:115]
	v_mfma_f32_16x16x32_bf16 v[108:111], v[180:183], v[212:215], v[108:111]
	v_mfma_f32_16x16x32_bf16 v[104:107], v[188:191], v[212:215], v[104:107]
	v_mfma_f32_16x16x32_bf16 v[100:103], v[180:183], v[220:223], v[100:103]
	v_mfma_f32_16x16x32_bf16 v[96:99], v[188:191], v[220:223], v[96:99]
	s_barrier
	s_add_u32 m0, s35, 0x10000
	ds_read_b128 v[224:227], v164 offset:16384
	ds_read_b128 v[228:231], v164 offset:17408
	ds_read_b128 v[232:235], v164 offset:18432
	ds_read_b128 v[236:239], v164 offset:19456
	global_load_lds_dwordx4 v128, s[42:43]
	s_add_u32 m0, s35, 0x12000
	s_nop 0
	global_load_lds_dwordx4 v130, s[42:43]
	s_add_u32 s42, s42, 0x80
	s_addc_u32 s43, s43, 0
	s_add_i32 s34, s34, 2
	s_barrier
	s_waitcnt lgkmcnt(0)
	v_mfma_f32_16x16x32_bf16 v[92:95], v[224:227], v[192:195], v[92:95]
	v_mfma_f32_16x16x32_bf16 v[88:91], v[232:235], v[192:195], v[88:91]
	v_mfma_f32_16x16x32_bf16 v[84:87], v[224:227], v[200:203], v[84:87]
	v_mfma_f32_16x16x32_bf16 v[80:83], v[232:235], v[200:203], v[80:83]
	v_mfma_f32_16x16x32_bf16 v[76:79], v[224:227], v[208:211], v[76:79]
	v_mfma_f32_16x16x32_bf16 v[72:75], v[232:235], v[208:211], v[72:75]
	v_mfma_f32_16x16x32_bf16 v[68:71], v[224:227], v[216:219], v[68:71]
	v_mfma_f32_16x16x32_bf16 v[64:67], v[232:235], v[216:219], v[64:67]
	v_mfma_f32_16x16x32_bf16 v[92:95], v[228:231], v[196:199], v[92:95]
	v_mfma_f32_16x16x32_bf16 v[88:91], v[236:239], v[196:199], v[88:91]
	v_mfma_f32_16x16x32_bf16 v[84:87], v[228:231], v[204:207], v[84:87]
	v_mfma_f32_16x16x32_bf16 v[80:83], v[236:239], v[204:207], v[80:83]
	v_mfma_f32_16x16x32_bf16 v[76:79], v[228:231], v[212:215], v[76:79]
	v_mfma_f32_16x16x32_bf16 v[72:75], v[236:239], v[212:215], v[72:75]
	v_mfma_f32_16x16x32_bf16 v[68:71], v[228:231], v[220:223], v[68:71]
	v_mfma_f32_16x16x32_bf16 v[64:67], v[236:239], v[220:223], v[64:67]
	s_barrier
	s_add_u32 m0, s35, 0x0
	ds_read_b128 v[192:195], v162 offset:16384
	ds_read_b128 v[196:199], v162 offset:17408
	ds_read_b128 v[200:203], v162 offset:18432
	ds_read_b128 v[204:207], v162 offset:19456
	ds_read_b128 v[208:211], v162 offset:20480
	ds_read_b128 v[212:215], v162 offset:21504
	ds_read_b128 v[216:219], v162 offset:22528
	ds_read_b128 v[220:223], v162 offset:23552
	global_load_lds_dwordx4 v128, s[72:73]
	s_add_u32 m0, s35, 0x2000
	s_nop 0
	global_load_lds_dwordx4 v130, s[72:73]
	s_add_u32 s72, s72, 0x80
	s_addc_u32 s73, s73, 0
	s_barrier
	s_waitcnt lgkmcnt(0)
	v_mfma_f32_16x16x32_bf16 v[60:63], v[176:179], v[192:195], v[60:63]
	v_mfma_f32_16x16x32_bf16 v[56:59], v[184:187], v[192:195], v[56:59]
	v_mfma_f32_16x16x32_bf16 v[52:55], v[176:179], v[200:203], v[52:55]
	v_mfma_f32_16x16x32_bf16 v[48:51], v[184:187], v[200:203], v[48:51]
	v_mfma_f32_16x16x32_bf16 v[44:47], v[176:179], v[208:211], v[44:47]
	v_mfma_f32_16x16x32_bf16 v[40:43], v[184:187], v[208:211], v[40:43]
	v_mfma_f32_16x16x32_bf16 v[36:39], v[176:179], v[216:219], v[36:39]
	v_mfma_f32_16x16x32_bf16 v[32:35], v[184:187], v[216:219], v[32:35]
	v_mfma_f32_16x16x32_bf16 v[60:63], v[180:183], v[196:199], v[60:63]
	v_mfma_f32_16x16x32_bf16 v[56:59], v[188:191], v[196:199], v[56:59]
	v_mfma_f32_16x16x32_bf16 v[52:55], v[180:183], v[204:207], v[52:55]
	v_mfma_f32_16x16x32_bf16 v[48:51], v[188:191], v[204:207], v[48:51]
	v_mfma_f32_16x16x32_bf16 v[44:47], v[180:183], v[212:215], v[44:47]
	v_mfma_f32_16x16x32_bf16 v[40:43], v[188:191], v[212:215], v[40:43]
	v_mfma_f32_16x16x32_bf16 v[36:39], v[180:183], v[220:223], v[36:39]
	v_mfma_f32_16x16x32_bf16 v[32:35], v[188:191], v[220:223], v[32:35]
	s_barrier
	s_add_u32 m0, s35, 0x14000
	s_nop 0
	global_load_lds_dwordx4 v128, s[78:79]
	s_add_u32 m0, s35, 0x16000
	s_nop 0
	global_load_lds_dwordx4 v130, s[78:79]
	s_add_u32 s78, s78, 0x80
	s_addc_u32 s79, s79, 0
	s_waitcnt vmcnt(6)
	s_barrier
	v_mfma_f32_16x16x32_bf16 v[28:31], v[224:227], v[192:195], v[28:31]
	v_mfma_f32_16x16x32_bf16 v[24:27], v[232:235], v[192:195], v[24:27]
	v_mfma_f32_16x16x32_bf16 v[20:23], v[224:227], v[200:203], v[20:23]
	v_mfma_f32_16x16x32_bf16 v[16:19], v[232:235], v[200:203], v[16:19]
	v_mfma_f32_16x16x32_bf16 v[12:15], v[224:227], v[208:211], v[12:15]
	v_mfma_f32_16x16x32_bf16 v[8:11], v[232:235], v[208:211], v[8:11]
	v_mfma_f32_16x16x32_bf16 v[4:7], v[224:227], v[216:219], v[4:7]
	v_mfma_f32_16x16x32_bf16 v[0:3], v[232:235], v[216:219], v[0:3]
	v_mfma_f32_16x16x32_bf16 v[28:31], v[228:231], v[196:199], v[28:31]
	v_mfma_f32_16x16x32_bf16 v[24:27], v[236:239], v[196:199], v[24:27]
	v_mfma_f32_16x16x32_bf16 v[20:23], v[228:231], v[204:207], v[20:23]
	v_mfma_f32_16x16x32_bf16 v[16:19], v[236:239], v[204:207], v[16:19]
	v_mfma_f32_16x16x32_bf16 v[12:15], v[228:231], v[212:215], v[12:15]
	v_mfma_f32_16x16x32_bf16 v[8:11], v[236:239], v[212:215], v[8:11]
	v_mfma_f32_16x16x32_bf16 v[4:7], v[228:231], v[220:223], v[4:7]
	v_mfma_f32_16x16x32_bf16 v[0:3], v[236:239], v[220:223], v[0:3]
	s_barrier
	s_add_u32 m0, s35, 0x4000
	ds_read_b128 v[176:179], v164 offset:32768
	ds_read_b128 v[180:183], v164 offset:33792
	ds_read_b128 v[184:187], v164 offset:34816
	ds_read_b128 v[188:191], v164 offset:35840
	ds_read_b128 v[192:195], v162 offset:32768
	ds_read_b128 v[196:199], v162 offset:33792
	ds_read_b128 v[200:203], v162 offset:34816
	ds_read_b128 v[204:207], v162 offset:35840
	ds_read_b128 v[208:211], v162 offset:36864
	ds_read_b128 v[212:215], v162 offset:37888
	ds_read_b128 v[216:219], v162 offset:38912
	ds_read_b128 v[220:223], v162 offset:39936
	global_load_lds_dwordx4 v128, s[76:77]
	s_add_u32 m0, s35, 0x6000
	s_nop 0
	global_load_lds_dwordx4 v130, s[76:77]
	s_add_u32 s76, s76, 0x80
	s_addc_u32 s77, s77, 0
	s_waitcnt lgkmcnt(8)
	s_barrier
	s_waitcnt lgkmcnt(0)
	v_mfma_f32_16x16x32_bf16 v[124:127], v[176:179], v[192:195], v[124:127]
	v_mfma_f32_16x16x32_bf16 v[120:123], v[184:187], v[192:195], v[120:123]
	v_mfma_f32_16x16x32_bf16 v[116:119], v[176:179], v[200:203], v[116:119]
	v_mfma_f32_16x16x32_bf16 v[112:115], v[184:187], v[200:203], v[112:115]
	v_mfma_f32_16x16x32_bf16 v[108:111], v[176:179], v[208:211], v[108:111]
	v_mfma_f32_16x16x32_bf16 v[104:107], v[184:187], v[208:211], v[104:107]
	v_mfma_f32_16x16x32_bf16 v[100:103], v[176:179], v[216:219], v[100:103]
	v_mfma_f32_16x16x32_bf16 v[96:99], v[184:187], v[216:219], v[96:99]
	v_mfma_f32_16x16x32_bf16 v[124:127], v[180:183], v[196:199], v[124:127]
	v_mfma_f32_16x16x32_bf16 v[120:123], v[188:191], v[196:199], v[120:123]
	v_mfma_f32_16x16x32_bf16 v[116:119], v[180:183], v[204:207], v[116:119]
	v_mfma_f32_16x16x32_bf16 v[112:115], v[188:191], v[204:207], v[112:115]
	v_mfma_f32_16x16x32_bf16 v[108:111], v[180:183], v[212:215], v[108:111]
	v_mfma_f32_16x16x32_bf16 v[104:107], v[188:191], v[212:215], v[104:107]
	v_mfma_f32_16x16x32_bf16 v[100:103], v[180:183], v[220:223], v[100:103]
	v_mfma_f32_16x16x32_bf16 v[96:99], v[188:191], v[220:223], v[96:99]
	s_barrier
	s_add_u32 m0, s35, 0x18000
	ds_read_b128 v[224:227], v164 offset:49152
	ds_read_b128 v[228:231], v164 offset:50176
	ds_read_b128 v[232:235], v164 offset:51200
	ds_read_b128 v[236:239], v164 offset:52224
	global_load_lds_dwordx4 v128, s[42:43]
	s_add_u32 m0, s35, 0x1a000
	s_nop 0
	global_load_lds_dwordx4 v130, s[42:43]
	s_add_u32 s42, s42, 0x80
	s_addc_u32 s43, s43, 0
	s_barrier
	s_waitcnt lgkmcnt(0)
	v_mfma_f32_16x16x32_bf16 v[92:95], v[224:227], v[192:195], v[92:95]
	v_mfma_f32_16x16x32_bf16 v[88:91], v[232:235], v[192:195], v[88:91]
	v_mfma_f32_16x16x32_bf16 v[84:87], v[224:227], v[200:203], v[84:87]
	v_mfma_f32_16x16x32_bf16 v[80:83], v[232:235], v[200:203], v[80:83]
	v_mfma_f32_16x16x32_bf16 v[76:79], v[224:227], v[208:211], v[76:79]
	v_mfma_f32_16x16x32_bf16 v[72:75], v[232:235], v[208:211], v[72:75]
	v_mfma_f32_16x16x32_bf16 v[68:71], v[224:227], v[216:219], v[68:71]
	v_mfma_f32_16x16x32_bf16 v[64:67], v[232:235], v[216:219], v[64:67]
	v_mfma_f32_16x16x32_bf16 v[92:95], v[228:231], v[196:199], v[92:95]
	v_mfma_f32_16x16x32_bf16 v[88:91], v[236:239], v[196:199], v[88:91]
	v_mfma_f32_16x16x32_bf16 v[84:87], v[228:231], v[204:207], v[84:87]
	v_mfma_f32_16x16x32_bf16 v[80:83], v[236:239], v[204:207], v[80:83]
	v_mfma_f32_16x16x32_bf16 v[76:79], v[228:231], v[212:215], v[76:79]
	v_mfma_f32_16x16x32_bf16 v[72:75], v[236:239], v[212:215], v[72:75]
	v_mfma_f32_16x16x32_bf16 v[68:71], v[228:231], v[220:223], v[68:71]
	v_mfma_f32_16x16x32_bf16 v[64:67], v[236:239], v[220:223], v[64:67]
	s_barrier
	s_add_u32 m0, s35, 0x8000
	ds_read_b128 v[192:195], v162 offset:49152
	ds_read_b128 v[196:199], v162 offset:50176
	ds_read_b128 v[200:203], v162 offset:51200
	ds_read_b128 v[204:207], v162 offset:52224
	ds_read_b128 v[208:211], v162 offset:53248
	ds_read_b128 v[212:215], v162 offset:54272
	ds_read_b128 v[216:219], v162 offset:55296
	ds_read_b128 v[220:223], v162 offset:56320
	global_load_lds_dwordx4 v128, s[72:73]
	s_add_u32 m0, s35, 0xa000
	s_nop 0
	global_load_lds_dwordx4 v130, s[72:73]
	s_add_u32 s72, s72, 0x80
	s_addc_u32 s73, s73, 0
	s_barrier
	s_waitcnt lgkmcnt(0)
	v_mfma_f32_16x16x32_bf16 v[60:63], v[176:179], v[192:195], v[60:63]
	v_mfma_f32_16x16x32_bf16 v[56:59], v[184:187], v[192:195], v[56:59]
	v_mfma_f32_16x16x32_bf16 v[52:55], v[176:179], v[200:203], v[52:55]
	v_mfma_f32_16x16x32_bf16 v[48:51], v[184:187], v[200:203], v[48:51]
	v_mfma_f32_16x16x32_bf16 v[44:47], v[176:179], v[208:211], v[44:47]
	v_mfma_f32_16x16x32_bf16 v[40:43], v[184:187], v[208:211], v[40:43]
	v_mfma_f32_16x16x32_bf16 v[36:39], v[176:179], v[216:219], v[36:39]
	v_mfma_f32_16x16x32_bf16 v[32:35], v[184:187], v[216:219], v[32:35]
	v_mfma_f32_16x16x32_bf16 v[60:63], v[180:183], v[196:199], v[60:63]
	v_mfma_f32_16x16x32_bf16 v[56:59], v[188:191], v[196:199], v[56:59]
	v_mfma_f32_16x16x32_bf16 v[52:55], v[180:183], v[204:207], v[52:55]
	v_mfma_f32_16x16x32_bf16 v[48:51], v[188:191], v[204:207], v[48:51]
	v_mfma_f32_16x16x32_bf16 v[44:47], v[180:183], v[212:215], v[44:47]
	v_mfma_f32_16x16x32_bf16 v[40:43], v[188:191], v[212:215], v[40:43]
	v_mfma_f32_16x16x32_bf16 v[36:39], v[180:183], v[220:223], v[36:39]
	v_mfma_f32_16x16x32_bf16 v[32:35], v[188:191], v[220:223], v[32:35]
	s_barrier
	s_add_u32 m0, s35, 0x1c000
	s_nop 0
	global_load_lds_dwordx4 v128, s[78:79]
	s_add_u32 m0, s35, 0x1e000
	s_nop 0
	global_load_lds_dwordx4 v130, s[78:79]
	s_add_u32 s78, s78, 0x80
	s_addc_u32 s79, s79, 0
	s_waitcnt vmcnt(6)
	s_barrier
	v_mfma_f32_16x16x32_bf16 v[28:31], v[224:227], v[192:195], v[28:31]
	v_mfma_f32_16x16x32_bf16 v[24:27], v[232:235], v[192:195], v[24:27]
	v_mfma_f32_16x16x32_bf16 v[20:23], v[224:227], v[200:203], v[20:23]
	v_mfma_f32_16x16x32_bf16 v[16:19], v[232:235], v[200:203], v[16:19]
	v_mfma_f32_16x16x32_bf16 v[12:15], v[224:227], v[208:211], v[12:15]
	v_mfma_f32_16x16x32_bf16 v[8:11], v[232:235], v[208:211], v[8:11]
	v_mfma_f32_16x16x32_bf16 v[4:7], v[224:227], v[216:219], v[4:7]
	v_mfma_f32_16x16x32_bf16 v[0:3], v[232:235], v[216:219], v[0:3]
	v_mfma_f32_16x16x32_bf16 v[28:31], v[228:231], v[196:199], v[28:31]
	v_mfma_f32_16x16x32_bf16 v[24:27], v[236:239], v[196:199], v[24:27]
	v_mfma_f32_16x16x32_bf16 v[20:23], v[228:231], v[204:207], v[20:23]
	v_mfma_f32_16x16x32_bf16 v[16:19], v[236:239], v[204:207], v[16:19]
	v_mfma_f32_16x16x32_bf16 v[12:15], v[228:231], v[212:215], v[12:15]
	v_mfma_f32_16x16x32_bf16 v[8:11], v[236:239], v[212:215], v[8:11]
	v_mfma_f32_16x16x32_bf16 v[4:7], v[228:231], v[220:223], v[4:7]
	v_mfma_f32_16x16x32_bf16 v[0:3], v[236:239], v[220:223], v[0:3]
	s_cmp_lt_u32 s34, s3
	s_barrier
	s_cbranch_scc1 .LBB0_187
	s_setprio 0
	s_mov_b64 s[72:73], 0x80
	s_mov_b64 s[76:77], 0x100
	s_mov_b64 s[78:79], 0x180
	s_add_i32 s66, s2, -1
	s_lshl_b64 s[2:3], s[66:67], 7
	s_add_u32 s2, s54, s2
	s_addc_u32 s3, s55, s3
	v_readfirstlane_b32 s34, v174
	v_lshl_add_u64 v[150:151], s[2:3], 0, v[128:129]
	s_mov_b32 m0, s34
	v_lshl_add_u64 v[130:131], s[2:3], 0, v[130:131]
	v_readfirstlane_b32 s2, v175
	ds_read_b128 v[132:135], v164
	ds_read_b128 v[136:139], v164 offset:1024
	ds_read_b128 v[140:143], v164 offset:2048
	ds_read_b128 v[144:147], v164 offset:3072
	ds_read_b128 v[158:161], v162
	ds_read_b128 v[166:169], v162 offset:1024
	ds_read_b128 v[170:173], v162 offset:2048
	ds_read_b128 v[176:179], v162 offset:3072
	ds_read_b128 v[180:183], v162 offset:4096
	ds_read_b128 v[184:187], v162 offset:5120
	ds_read_b128 v[188:191], v162 offset:6144
	ds_read_b128 v[192:195], v162 offset:7168
	global_load_lds_dwordx4 v[150:151], off
	s_mov_b32 m0, s2
	s_nop 0
	global_load_lds_dwordx4 v[130:131], off
	s_barrier
	s_waitcnt lgkmcnt(0)
	s_setprio 1
	s_waitcnt lgkmcnt(0)
	v_mfma_f32_16x16x32_bf16 v[124:127], v[132:135], v[158:161], v[124:127]
	v_mfma_f32_16x16x32_bf16 v[120:123], v[140:143], v[158:161], v[120:123]
	v_mfma_f32_16x16x32_bf16 v[116:119], v[132:135], v[170:173], v[116:119]
	v_mfma_f32_16x16x32_bf16 v[112:115], v[140:143], v[170:173], v[112:115]
	v_mfma_f32_16x16x32_bf16 v[100:103], v[132:135], v[188:191], v[100:103]
	v_mfma_f32_16x16x32_bf16 v[96:99], v[140:143], v[188:191], v[96:99]
	v_mfma_f32_16x16x32_bf16 v[124:127], v[136:139], v[166:169], v[124:127]
	v_mfma_f32_16x16x32_bf16 v[120:123], v[144:147], v[166:169], v[120:123]
	v_mfma_f32_16x16x32_bf16 v[116:119], v[136:139], v[176:179], v[116:119]
	v_mfma_f32_16x16x32_bf16 v[112:115], v[144:147], v[176:179], v[112:115]
	v_mfma_f32_16x16x32_bf16 v[108:111], v[132:135], v[180:183], v[108:111]
	v_mfma_f32_16x16x32_bf16 v[104:107], v[140:143], v[180:183], v[104:107]
	v_mfma_f32_16x16x32_bf16 v[100:103], v[136:139], v[192:195], v[100:103]
	v_mfma_f32_16x16x32_bf16 v[96:99], v[144:147], v[192:195], v[96:99]
	v_mfma_f32_16x16x32_bf16 v[196:199], v[136:139], v[184:187], v[108:111]
	v_mfma_f32_16x16x32_bf16 v[200:203], v[144:147], v[184:187], v[104:107]
	s_setprio 0
	s_barrier
	s_nop 1
	ds_read_b128 v[104:107], v164 offset:16384
	ds_read_b128 v[108:111], v164 offset:17408
	ds_read_b128 v[204:207], v164 offset:18432
	ds_read_b128 v[208:211], v164 offset:19456
	s_barrier
	s_waitcnt lgkmcnt(0)
	s_setprio 1
	s_waitcnt lgkmcnt(0)
	v_mfma_f32_16x16x32_bf16 v[84:87], v[104:107], v[170:173], v[84:87]
	v_mfma_f32_16x16x32_bf16 v[80:83], v[204:207], v[170:173], v[80:83]
	v_mfma_f32_16x16x32_bf16 v[68:71], v[104:107], v[188:191], v[68:71]
	v_mfma_f32_16x16x32_bf16 v[64:67], v[204:207], v[188:191], v[64:67]
	v_mfma_f32_16x16x32_bf16 v[92:95], v[104:107], v[158:161], v[92:95]
	v_mfma_f32_16x16x32_bf16 v[88:91], v[204:207], v[158:161], v[88:91]
	v_mfma_f32_16x16x32_bf16 v[84:87], v[108:111], v[176:179], v[84:87]
	v_mfma_f32_16x16x32_bf16 v[80:83], v[208:211], v[176:179], v[80:83]
	v_mfma_f32_16x16x32_bf16 v[76:79], v[104:107], v[180:183], v[76:79]
	v_mfma_f32_16x16x32_bf16 v[72:75], v[204:207], v[180:183], v[72:75]
	v_mfma_f32_16x16x32_bf16 v[68:71], v[108:111], v[192:195], v[68:71]
	v_mfma_f32_16x16x32_bf16 v[64:67], v[208:211], v[192:195], v[64:67]
	v_mfma_f32_16x16x32_bf16 v[212:215], v[108:111], v[166:169], v[92:95]
	v_mfma_f32_16x16x32_bf16 v[158:161], v[208:211], v[166:169], v[88:91]
	v_mfma_f32_16x16x32_bf16 v[166:169], v[108:111], v[184:187], v[76:79]
	v_mfma_f32_16x16x32_bf16 v[170:173], v[208:211], v[184:187], v[72:75]
	s_setprio 0
	s_barrier
	s_nop 0
	ds_read_b128 v[72:75], v162 offset:16384
	ds_read_b128 v[76:79], v162 offset:17408
	ds_read_b128 v[88:91], v162 offset:18432
	ds_read_b128 v[92:95], v162 offset:19456
	ds_read_b128 v[174:177], v162 offset:20480
	ds_read_b128 v[178:181], v162 offset:21504
	ds_read_b128 v[182:185], v162 offset:22528
	ds_read_b128 v[186:189], v162 offset:23552
	s_waitcnt vmcnt(4)
	s_barrier
	s_waitcnt lgkmcnt(0)
	s_setprio 1
	s_waitcnt lgkmcnt(0)
	v_mfma_f32_16x16x32_bf16 v[60:63], v[132:135], v[72:75], v[60:63]
	v_mfma_f32_16x16x32_bf16 v[56:59], v[140:143], v[72:75], v[56:59]
	v_mfma_f32_16x16x32_bf16 v[52:55], v[132:135], v[88:91], v[52:55]
	v_mfma_f32_16x16x32_bf16 v[48:51], v[140:143], v[88:91], v[48:51]
	v_mfma_f32_16x16x32_bf16 v[36:39], v[132:135], v[182:185], v[36:39]
	v_mfma_f32_16x16x32_bf16 v[32:35], v[140:143], v[182:185], v[32:35]
	v_mfma_f32_16x16x32_bf16 v[60:63], v[136:139], v[76:79], v[60:63]
	v_mfma_f32_16x16x32_bf16 v[56:59], v[144:147], v[76:79], v[56:59]
	v_mfma_f32_16x16x32_bf16 v[52:55], v[136:139], v[92:95], v[52:55]
	v_mfma_f32_16x16x32_bf16 v[48:51], v[144:147], v[92:95], v[48:51]
	v_mfma_f32_16x16x32_bf16 v[44:47], v[132:135], v[174:177], v[44:47]
	v_mfma_f32_16x16x32_bf16 v[40:43], v[140:143], v[174:177], v[40:43]
	v_mfma_f32_16x16x32_bf16 v[36:39], v[136:139], v[186:189], v[36:39]
	v_mfma_f32_16x16x32_bf16 v[32:35], v[144:147], v[186:189], v[32:35]
	v_mfma_f32_16x16x32_bf16 v[190:193], v[136:139], v[178:181], v[44:47]
	v_mfma_f32_16x16x32_bf16 v[216:219], v[144:147], v[178:181], v[40:43]
	s_setprio 0
	s_setprio 1
	v_mfma_f32_16x16x32_bf16 v[20:23], v[104:107], v[88:91], v[20:23]
	v_mfma_f32_16x16x32_bf16 v[16:19], v[204:207], v[88:91], v[16:19]
	v_mfma_f32_16x16x32_bf16 v[4:7], v[104:107], v[182:185], v[4:7]
	v_mfma_f32_16x16x32_bf16 v[0:3], v[204:207], v[182:185], v[0:3]
	v_mfma_f32_16x16x32_bf16 v[28:31], v[104:107], v[72:75], v[28:31]
	v_mfma_f32_16x16x32_bf16 v[24:27], v[204:207], v[72:75], v[24:27]
	v_mfma_f32_16x16x32_bf16 v[20:23], v[108:111], v[92:95], v[20:23]
	v_mfma_f32_16x16x32_bf16 v[16:19], v[208:211], v[92:95], v[16:19]
	v_mfma_f32_16x16x32_bf16 v[12:15], v[104:107], v[174:177], v[12:15]
	v_mfma_f32_16x16x32_bf16 v[8:11], v[204:207], v[174:177], v[8:11]
	v_mfma_f32_16x16x32_bf16 v[4:7], v[108:111], v[186:189], v[4:7]
	v_mfma_f32_16x16x32_bf16 v[0:3], v[208:211], v[186:189], v[0:3]
	v_mfma_f32_16x16x32_bf16 v[130:133], v[108:111], v[76:79], v[28:31]
	v_mfma_f32_16x16x32_bf16 v[134:137], v[208:211], v[76:79], v[24:27]
	v_mfma_f32_16x16x32_bf16 v[138:141], v[108:111], v[178:181], v[12:15]
	v_mfma_f32_16x16x32_bf16 v[142:145], v[208:211], v[178:181], v[8:11]
	s_setprio 0
	s_barrier
	s_nop 0
	ds_read_b128 v[8:11], v164 offset:32768
	ds_read_b128 v[12:15], v164 offset:33792
	ds_read_b128 v[174:177], v164 offset:34816
	ds_read_b128 v[178:181], v164 offset:35840
	ds_read_b128 v[24:27], v162 offset:32768
	ds_read_b128 v[28:31], v162 offset:33792
	ds_read_b128 v[40:43], v162 offset:34816
	ds_read_b128 v[44:47], v162 offset:35840
	ds_read_b128 v[182:185], v162 offset:36864
	ds_read_b128 v[186:189], v162 offset:37888
	ds_read_b128 v[204:207], v162 offset:38912
	ds_read_b128 v[208:211], v162 offset:39936
	s_waitcnt vmcnt(2)
	s_barrier
	s_waitcnt lgkmcnt(0)
	s_setprio 1
	s_waitcnt lgkmcnt(0)
	v_mfma_f32_16x16x32_bf16 v[72:75], v[8:11], v[24:27], v[124:127]
	v_mfma_f32_16x16x32_bf16 v[124:127], v[12:15], v[28:31], v[72:75]
	v_mfma_f32_16x16x32_bf16 v[72:75], v[174:177], v[24:27], v[120:123]
	v_mfma_f32_16x16x32_bf16 v[120:123], v[178:181], v[28:31], v[72:75]
	v_mfma_f32_16x16x32_bf16 v[72:75], v[8:11], v[40:43], v[116:119]
	v_mfma_f32_16x16x32_bf16 v[108:111], v[12:15], v[44:47], v[72:75]
	v_mfma_f32_16x16x32_bf16 v[72:75], v[174:177], v[40:43], v[112:115]
	v_mfma_f32_16x16x32_bf16 v[104:107], v[178:181], v[44:47], v[72:75]
	v_mfma_f32_16x16x32_bf16 v[72:75], v[8:11], v[182:185], v[196:199]
	v_mfma_f32_16x16x32_bf16 v[92:95], v[12:15], v[186:189], v[72:75]
	v_mfma_f32_16x16x32_bf16 v[72:75], v[174:177], v[182:185], v[200:203]
	v_mfma_f32_16x16x32_bf16 v[88:91], v[178:181], v[186:189], v[72:75]
	v_mfma_f32_16x16x32_bf16 v[72:75], v[8:11], v[204:207], v[100:103]
	v_mfma_f32_16x16x32_bf16 v[76:79], v[12:15], v[208:211], v[72:75]
	v_mfma_f32_16x16x32_bf16 v[72:75], v[174:177], v[204:207], v[96:99]
	v_mfma_f32_16x16x32_bf16 v[72:75], v[178:181], v[208:211], v[72:75]
	s_setprio 0
	s_barrier
	ds_read_b128 v[194:197], v164 offset:49152
	ds_read_b128 v[198:201], v164 offset:50176
	ds_read_b128 v[220:223], v164 offset:51200
	ds_read_b128 v[224:227], v164 offset:52224
	s_waitcnt vmcnt(0)
	s_barrier
	s_waitcnt lgkmcnt(0)
	s_setprio 1
	s_waitcnt lgkmcnt(0)
	v_mfma_f32_16x16x32_bf16 v[96:99], v[194:197], v[24:27], v[212:215]
	v_mfma_f32_16x16x32_bf16 v[24:27], v[220:223], v[24:27], v[158:161]
	v_mfma_f32_16x16x32_bf16 v[112:115], v[224:227], v[28:31], v[24:27]
	v_mfma_f32_16x16x32_bf16 v[24:27], v[194:197], v[40:43], v[84:87]
	v_mfma_f32_16x16x32_bf16 v[100:103], v[198:201], v[44:47], v[24:27]
	v_mfma_f32_16x16x32_bf16 v[24:27], v[220:223], v[40:43], v[80:83]
	v_mfma_f32_16x16x32_bf16 v[116:119], v[198:201], v[28:31], v[96:99]
	v_mfma_f32_16x16x32_bf16 v[96:99], v[224:227], v[44:47], v[24:27]
	v_mfma_f32_16x16x32_bf16 v[24:27], v[194:197], v[182:185], v[166:169]
	v_mfma_f32_16x16x32_bf16 v[84:87], v[198:201], v[186:189], v[24:27]
	v_mfma_f32_16x16x32_bf16 v[24:27], v[220:223], v[182:185], v[170:173]
	v_mfma_f32_16x16x32_bf16 v[80:83], v[224:227], v[186:189], v[24:27]
	v_mfma_f32_16x16x32_bf16 v[24:27], v[194:197], v[204:207], v[68:71]
	v_mfma_f32_16x16x32_bf16 v[68:71], v[198:201], v[208:211], v[24:27]
	v_mfma_f32_16x16x32_bf16 v[24:27], v[220:223], v[204:207], v[64:67]
	v_mfma_f32_16x16x32_bf16 v[64:67], v[224:227], v[208:211], v[24:27]
	s_setprio 0
	s_barrier
	ds_read_b128 v[158:161], v162 offset:49152
	ds_read_b128 v[164:167], v162 offset:50176
	ds_read_b128 v[168:171], v162 offset:51200
	ds_read_b128 v[182:185], v162 offset:52224
	ds_read_b128 v[186:189], v162 offset:53248
	ds_read_b128 v[202:205], v162 offset:54272
	ds_read_b128 v[206:209], v162 offset:55296
	ds_read_b128 v[210:213], v162 offset:56320
	s_barrier
	s_waitcnt lgkmcnt(0)
	s_setprio 1
	s_waitcnt lgkmcnt(0)
	v_mfma_f32_16x16x32_bf16 v[24:27], v[8:11], v[158:161], v[60:63]
	v_mfma_f32_16x16x32_bf16 v[60:63], v[12:15], v[164:167], v[24:27]
	v_mfma_f32_16x16x32_bf16 v[24:27], v[174:177], v[158:161], v[56:59]
	v_mfma_f32_16x16x32_bf16 v[56:59], v[178:181], v[164:167], v[24:27]
	v_mfma_f32_16x16x32_bf16 v[24:27], v[8:11], v[168:171], v[52:55]
	v_mfma_f32_16x16x32_bf16 v[44:47], v[12:15], v[182:185], v[24:27]
	v_mfma_f32_16x16x32_bf16 v[24:27], v[174:177], v[168:171], v[48:51]
	v_mfma_f32_16x16x32_bf16 v[40:43], v[178:181], v[182:185], v[24:27]
	v_mfma_f32_16x16x32_bf16 v[24:27], v[8:11], v[186:189], v[190:193]
	v_mfma_f32_16x16x32_bf16 v[8:11], v[8:11], v[206:209], v[36:39]
	v_mfma_f32_16x16x32_bf16 v[28:31], v[12:15], v[202:205], v[24:27]
	v_mfma_f32_16x16x32_bf16 v[24:27], v[174:177], v[186:189], v[216:219]
	v_mfma_f32_16x16x32_bf16 v[12:15], v[12:15], v[210:213], v[8:11]
	v_mfma_f32_16x16x32_bf16 v[8:11], v[174:177], v[206:209], v[32:35]
	v_mfma_f32_16x16x32_bf16 v[24:27], v[178:181], v[202:205], v[24:27]
	v_mfma_f32_16x16x32_bf16 v[8:11], v[178:181], v[210:213], v[8:11]
	s_setprio 0
	s_setprio 1
	v_mfma_f32_16x16x32_bf16 v[32:35], v[194:197], v[158:161], v[130:133]
	v_mfma_f32_16x16x32_bf16 v[52:55], v[198:201], v[164:167], v[32:35]
	v_mfma_f32_16x16x32_bf16 v[32:35], v[220:223], v[158:161], v[134:137]
	v_mfma_f32_16x16x32_bf16 v[16:19], v[220:223], v[168:171], v[16:19]
	v_mfma_f32_16x16x32_bf16 v[48:51], v[224:227], v[164:167], v[32:35]
	v_mfma_f32_16x16x32_bf16 v[20:23], v[194:197], v[168:171], v[20:23]
	v_mfma_f32_16x16x32_bf16 v[32:35], v[224:227], v[182:185], v[16:19]
	v_mfma_f32_16x16x32_bf16 v[16:19], v[194:197], v[186:189], v[138:141]
	v_mfma_f32_16x16x32_bf16 v[36:39], v[198:201], v[182:185], v[20:23]
	v_mfma_f32_16x16x32_bf16 v[20:23], v[198:201], v[202:205], v[16:19]
	v_mfma_f32_16x16x32_bf16 v[16:19], v[220:223], v[186:189], v[142:145]
	v_mfma_f32_16x16x32_bf16 v[4:7], v[194:197], v[206:209], v[4:7]
	v_mfma_f32_16x16x32_bf16 v[0:3], v[220:223], v[206:209], v[0:3]
	v_mfma_f32_16x16x32_bf16 v[16:19], v[224:227], v[202:205], v[16:19]
	v_mfma_f32_16x16x32_bf16 v[4:7], v[198:201], v[210:213], v[4:7]
	v_mfma_f32_16x16x32_bf16 v[0:3], v[224:227], v[210:213], v[0:3]
	s_setprio 0
	s_movk_i32 s2, 0x100
	v_cmp_gt_u32_e32 vcc, s2, v157
	s_barrier
	s_and_saveexec_b64 s[2:3], vcc
	s_cbranch_execz .LBB0_190
	s_barrier
